# MLA: tile DMA issue split, two pieces in the vector block and two at the start of the matrix block
# baseline (speedup 1.0000x reference)
; DI unsigned pk2(float lo, float hi) { const f32x2_t v = {lo, hi}; const bf16x2_t b = __builtin_convertvector(v, bf16x2_t); return __builtin_bit_cast(unsigned, b); }
; #define MLA_DMA(t, slot) do { _Pragma("unroll") for (int i_ = 0; i_ < 4; ++i_) { const bf16_t* src_ = (pisk[i_] ? kbase : vbase) + poff[i_] + (size_t)(t) * pstep[i_]; \
;         __builtin_amdgcn_global_load_lds((const unsigned*)src_, (LAS unsigned*)(lds + (slot) * SLOT + (w + 8 * i_) * 1024), 16, 0, 0); } } while (0)
; DI void mla_attn_phase(LAS unsigned char* lds, const bf16_t* Qg, const bf16_t* Kg, const bf16_t* Vtg, bf16_t* MIX) {
;     ...
;                 if (kt + 2 < NT) MLA_DMA(kt + 2, sl2);
;     ...
;                     const float m_new = fmaxf(m_run, mx), alpha = __builtin_amdgcn_exp2f(m_run - m_new); m_run = m_new;
;                     float sum = 0.f;
; #pragma unroll
;                     for (int i = 0; i < 16; ++i) { s0[i] = __builtin_amdgcn_exp2f(s0[i] - m_new); s1[i] = __builtin_amdgcn_exp2f(s1[i] - m_new); sum += s0[i] + s1[i]; }
;                     l_run = l_run * alpha + sum;
;                     if (__any(alpha != 1.f)) {
; #pragma unroll
;                         for (int mt = 0; mt < 4; ++mt)
; #pragma unroll
;                             for (int i = 0; i < 16; ++i) o[mt][i] *= alpha; }
;                     bf16x8 pf[4];
; #pragma unroll
;                     for (int sp = 0; sp < 2; ++sp) { u32x4 p0, p1;
; #pragma unroll
;                         for (int j = 0; j < 4; ++j) { p0[j] = pk2(s0[8 * sp + 2 * j], s0[8 * sp + 2 * j + 1]); p1[j] = pk2(s1[8 * sp + 2 * j], s1[8 * sp + 2 * j + 1]); }
;                         pf[sp] = __builtin_bit_cast(bf16x8, p0); pf[2 + sp] = __builtin_bit_cast(bf16x8, p1); }
.Lmla_dma:
	s_and_b64 vcc, exec, s[28:29]
	s_cbranch_vccnz .Lmla_nodma
	s_mov_b32 m0, s31
	s_nop 0
	global_load_lds_dwordx4 v[210:211], off
	s_add_i32 m0, s31, 0x2000
	s_nop 0
	global_load_lds_dwordx4 v[212:213], off
.Lmla_nodma:
	s_cmp_gt_i32 s40, s39
	s_cbranch_scc1 .Lmla_x
	v_sub_f32_e32 v80, v80, v3
	v_sub_f32_e32 v96, v96, v3
	v_exp_f32_e32 v80, v80
	v_exp_f32_e32 v96, v96
	v_sub_f32_e32 v81, v81, v3
	v_sub_f32_e32 v97, v97, v3
	v_exp_f32_e32 v81, v81
	v_exp_f32_e32 v97, v97
	v_sub_f32_e32 v82, v82, v3
	v_sub_f32_e32 v98, v98, v3
	v_exp_f32_e32 v82, v82
	v_exp_f32_e32 v98, v98
	v_sub_f32_e32 v83, v83, v3
	v_sub_f32_e32 v99, v99, v3
	v_exp_f32_e32 v83, v83
	v_exp_f32_e32 v99, v99
	v_add_f32_e32 v218, v80, v96
	v_sub_f32_e32 v84, v84, v3
	v_add_f32_e32 v218, 0, v218
	v_add_f32_e32 v219, v81, v97
	v_exp_f32_e32 v226, v84
	v_sub_f32_e32 v84, v100, v3
	v_add_f32_e32 v218, v219, v218
	v_add_f32_e32 v219, v82, v98
	v_exp_f32_e32 v100, v84
	v_sub_f32_e32 v84, v85, v3
	v_add_f32_e32 v218, v219, v218
	v_add_f32_e32 v219, v83, v99
	v_exp_f32_e32 v227, v84
	v_sub_f32_e32 v84, v101, v3
	v_sub_f32_e32 v86, v86, v3
	v_exp_f32_e32 v101, v84
	v_add_f32_e32 v84, v219, v218
	v_exp_f32_e32 v218, v86
	v_sub_f32_e32 v86, v102, v3
	v_exp_f32_e32 v102, v86
	v_sub_f32_e32 v86, v87, v3
	v_exp_f32_e32 v87, v86
	v_sub_f32_e32 v86, v103, v3
	v_exp_f32_e32 v103, v86
	v_sub_f32_e32 v86, v88, v3
	v_exp_f32_e32 v88, v86
	v_sub_f32_e32 v86, v104, v3
	v_exp_f32_e32 v104, v86
	v_sub_f32_e32 v86, v89, v3
	v_exp_f32_e32 v89, v86
	v_sub_f32_e32 v86, v105, v3
	v_exp_f32_e32 v105, v86
	v_sub_f32_e32 v86, v90, v3
	v_exp_f32_e32 v90, v86
	v_sub_f32_e32 v86, v106, v3
	v_exp_f32_e32 v106, v86
	v_sub_f32_e32 v86, v91, v3
	v_exp_f32_e32 v91, v86
	v_sub_f32_e32 v86, v107, v3
	v_exp_f32_e32 v107, v86
	v_sub_f32_e32 v86, v92, v3
	v_add_f32_e32 v85, v226, v100
	v_exp_f32_e32 v219, v86
	v_sub_f32_e32 v86, v108, v3
	v_add_f32_e32 v84, v85, v84
	v_add_f32_e32 v85, v227, v101
	v_exp_f32_e32 v108, v86
	v_sub_f32_e32 v86, v93, v3
	v_add_f32_e32 v84, v85, v84
	v_add_f32_e32 v85, v218, v102
	v_exp_f32_e32 v234, v86
	v_sub_f32_e32 v86, v109, v3
	v_add_f32_e32 v84, v85, v84
	v_add_f32_e32 v85, v87, v103
	v_exp_f32_e32 v109, v86
	v_sub_f32_e32 v86, v94, v3
	v_add_f32_e32 v84, v85, v84
	v_add_f32_e32 v85, v88, v104
	v_exp_f32_e32 v235, v86
	v_sub_f32_e32 v86, v110, v3
	v_add_f32_e32 v84, v85, v84
	v_add_f32_e32 v85, v89, v105
	v_exp_f32_e32 v110, v86
	v_sub_f32_e32 v86, v95, v3
	v_add_f32_e32 v84, v85, v84
	v_add_f32_e32 v85, v90, v106
	v_exp_f32_e32 v95, v86
	v_sub_f32_e32 v86, v111, v3
	v_add_f32_e32 v84, v85, v84
	v_add_f32_e32 v85, v91, v107
	v_exp_f32_e32 v111, v86
	v_add_f32_e32 v84, v85, v84
	v_add_f32_e32 v85, v219, v108
	v_add_f32_e32 v84, v85, v84
	v_add_f32_e32 v85, v234, v109
	v_add_f32_e32 v84, v85, v84
	v_add_f32_e32 v85, v235, v110
	v_add_f32_e32 v84, v85, v84
	v_add_f32_e32 v85, v95, v111
	v_add_f32_e32 v236, v85, v84
	v_fmac_f32_e32 v236, v233, v0
	v_cvt_pk_bf16_f32 v80, v80, v81
	v_cvt_pk_bf16_f32 v84, v96, v97
	v_cvt_pk_bf16_f32 v81, v82, v83
	v_cvt_pk_bf16_f32 v85, v98, v99
	v_cvt_pk_bf16_f32 v82, v226, v227
	v_cvt_pk_bf16_f32 v86, v100, v101
	v_cvt_pk_bf16_f32 v83, v218, v87
	v_cvt_pk_bf16_f32 v87, v102, v103
	v_cvt_pk_bf16_f32 v88, v88, v89
	v_cvt_pk_bf16_f32 v92, v104, v105
	v_cvt_pk_bf16_f32 v89, v90, v91
	v_cvt_pk_bf16_f32 v93, v106, v107
	v_cvt_pk_bf16_f32 v90, v219, v234
	v_cvt_pk_bf16_f32 v94, v108, v109
	v_cvt_pk_bf16_f32 v91, v235, v95
	v_cvt_pk_bf16_f32 v95, v110, v111
.Lmla_x:
	s_cmp_lt_u32 s34, 0x80
	s_cbranch_scc0 .Lmla_xb
	s_add_i32 s30, s42, 2
	s_cmp_ge_i32 s30, s38
	s_cbranch_scc1 .Lmla_xw0
	s_waitcnt vmcnt(2)
	s_branch .Lmla_xb

; #define MLA_DMA(t, slot) do { _Pragma("unroll") for (int i_ = 0; i_ < 4; ++i_) { const bf16_t* src_ = (pisk[i_] ? kbase : vbase) + poff[i_] + (size_t)(t) * pstep[i_]; \
;         __builtin_amdgcn_global_load_lds((const unsigned*)src_, (LAS unsigned*)(lds + (slot) * SLOT + (w + 8 * i_) * 1024), 16, 0, 0); } } while (0)
; DI void mla_attn_phase(LAS unsigned char* lds, const bf16_t* Qg, const bf16_t* Kg, const bf16_t* Vtg, bf16_t* MIX) {
;     ...
;                 if (kt + 2 < NT) MLA_DMA(kt + 2, sl2);
.Lmla_xb:
	s_barrier
	s_and_b64 vcc, exec, s[28:29]
	s_cbranch_vccnz .Lmla_nodma2
	s_add_i32 m0, s31, 0x4000
	s_nop 0
	global_load_lds_dwordx4 v[214:215], off
	s_add_i32 m0, s31, 0x6000
	s_nop 0
	global_load_lds_dwordx4 v[216:217], off
.Lmla_nodma2:
	s_cmp_gt_i32 s40, s39
	s_cbranch_scc1 .LBB0_367
	s_waitcnt lgkmcnt(6)
	v_mfma_f32_32x32x16_bf16 v[64:79], v[144:147], v[80:83], v[64:79]
	v_mfma_f32_32x32x16_bf16 v[48:63], v[140:143], v[80:83], v[48:63]
	s_waitcnt lgkmcnt(0)
	v_mfma_f32_32x32x16_bf16 v[32:47], v[148:151], v[80:83], v[32:47]
	v_mfma_f32_32x32x16_bf16 v[16:31], v[152:155], v[80:83], v[16:31]
	ds_read_b128 v[80:83], v1 offset:13376
	ds_read_b128 v[96:99], v1 offset:17984
	ds_read_b128 v[100:103], v1 offset:22592
	ds_read_b128 v[104:107], v1 offset:27200
	v_mfma_f32_32x32x16_bf16 v[64:79], v[136:139], v[88:91], v[64:79]
	v_mfma_f32_32x32x16_bf16 v[48:63], v[12:15], v[88:91], v[48:63]
	v_mfma_f32_32x32x16_bf16 v[32:47], v[4:7], v[88:91], v[32:47]
	v_mfma_f32_32x32x16_bf16 v[16:31], v[8:11], v[88:91], v[16:31]
	ds_read_b128 v[4:7], v1 offset:13408
	ds_read_b128 v[8:11], v1 offset:18016
	ds_read_b128 v[12:15], v1 offset:22624
	ds_read_b128 v[88:91], v1 offset:27232
	s_waitcnt lgkmcnt(4)
	v_mfma_f32_32x32x16_bf16 v[64:79], v[80:83], v[84:87], v[64:79]
	v_mov_b32_e32 v233, v236
	v_mfma_f32_32x32x16_bf16 v[48:63], v[96:99], v[84:87], v[48:63]
	v_mfma_f32_32x32x16_bf16 v[32:47], v[100:103], v[84:87], v[32:47]
	v_mfma_f32_32x32x16_bf16 v[16:31], v[104:107], v[84:87], v[16:31]
	s_waitcnt lgkmcnt(0)
	v_mfma_f32_32x32x16_bf16 v[64:79], v[4:7], v[92:95], v[64:79]
	v_mfma_f32_32x32x16_bf16 v[48:63], v[8:11], v[92:95], v[48:63]
	v_mfma_f32_32x32x16_bf16 v[32:47], v[12:15], v[92:95], v[32:47]
	v_mfma_f32_32x32x16_bf16 v[16:31], v[88:91], v[92:95], v[16:31]
	s_branch .LBB0_371
